# baseline (speedup 1.0000x reference)
; #define MFMA32(a, b, c) __builtin_amdgcn_mfma_f32_32x32x16_bf16((a), (b), (c), 0, 0, 0)
; template <int DQK, int MODE>
; DI void attn_core(const u16* __restrict__ Qg, int ldq, const u16* __restrict__ Kg, int ldk, const u16* __restrict__ Vtg,
;                   const u64* __restrict__ maskg, int q0, float scale, char* smem, int* sflags, f32x16 (&o)[4], float& l_run) {
;     ...
; #pragma unroll
;     for (int kt = 0; kt < 2; ++kt)
; #pragma unroll
;       for (int ks = 0; ks < NKS; ++ks) {
;         const bf16x8 kf = *(const bf16x8*)(Ks + (32 * kt + krow) * KSTR + ks * 16 + hh * 8);
;         s[kt] = MFMA32(kf, qf[ks], s[kt]);
;       }
;     ...
;       const bool need_mask = (tau * 64 + 63 >= q0 + 32 * wid);
;       float tot[4], otot[4];
; #pragma unroll
;       for (int c = 0; c < 4; ++c) {
;         const int kt = c >> 1, sb = (c & 1) * 8;
;         float run = 0.f;
; #pragma unroll
;         for (int j = 0; j < 8; ++j) {
;           const int i = sb + j;
;           const float z = s[kt][i] * scale;
;           s[kt][i] = z;
;           const float e = __builtin_amdgcn_exp2f(-fabsf(z) * LOG2E);
;           const float sp = fmaxf(z, 0.f) + LN2 * __builtin_amdgcn_logf(1.f + e);
;           bool valid = true;
;           if (need_mask) valid = (kbase + 32 * kt + 16 * (i >> 3) + (i & 7)) < qrow;
;           run += valid ? -sp : 0.f;
;         }
;         tot[c] = run;
;         otot[c] = __shfl_xor(run, 32);
.LBB0_214:
	s_andn2_b64 vcc, exec, s[4:5]
	s_cbranch_vccnz .LBB0_211
	v_add_u32_e32 v0, s87, v186
	v_mad_i64_i32 v[66:67], s[4:5], v0, s75, v[132:133]
	v_add_u32_e32 v0, s87, v185
	v_mad_i64_i32 v[70:71], s[4:5], v0, s75, v[134:135]
	global_load_dwordx4 v[66:69], v[66:67], off offset:3072
	s_nop 0
	global_load_dwordx4 v[70:73], v[70:71], off offset:3072
	s_nop 0
	global_load_dwordx4 v[74:77], v[136:137], off
	global_load_dwordx4 v[78:81], v[138:139], off
	s_add_i32 s4, s74, s87
	s_add_i32 s5, s4, 0x3bc0
	v_cmp_le_i32_e32 vcc, s5, v182
	s_waitcnt vmcnt(3)
	ds_write_b128 v187, v[66:69]
	s_waitcnt vmcnt(2)
	ds_write_b128 v206, v[70:73]
	s_waitcnt vmcnt(1)
	ds_write_b128 v207, v[74:77] offset:17408
	s_waitcnt vmcnt(0)
	ds_write_b128 v208, v[78:81] offset:17408
	s_waitcnt lgkmcnt(0)
	s_barrier
	s_and_saveexec_b64 s[6:7], vcc
	s_xor_b64 s[76:77], exec, s[6:7]
	s_cbranch_execz .LBB0_219
	ds_read_b128 v[150:153], v210
	ds_read_b128 v[156:159], v210 offset:32
	ds_read_b128 v[162:165], v210 offset:64
	ds_read_b128 v[166:169], v210 offset:96
	ds_read_b128 v[170:173], v210 offset:128
	ds_read_b128 v[174:177], v210 offset:160
	s_mov_b32 s18, 0xbfb8aa3b
	v_add_u32_e32 v140, s87, v184
	s_addk_i32 s4, 0x3bff
	s_waitcnt lgkmcnt(5)
	v_mfma_f32_32x32x16_bf16 v[82:97], v[150:153], v[98:101], 0
	ds_read_b128 v[150:153], v210 offset:192
	v_cmp_lt_i32_e64 s[4:5], s4, v181
	v_mbcnt_hi_u32_b32 v0, -1, v223
	v_add_u32_e32 v161, 0x3bc0, v140
	s_mov_b32 s68, 0x3f317218
	s_mov_b32 s33, 0xc2d00000
	s_waitcnt lgkmcnt(5)
	v_mfma_f32_32x32x16_bf16 v[82:97], v[156:159], v[102:105], v[82:97]
	ds_read_b128 v[156:159], v210 offset:224
	s_waitcnt lgkmcnt(5)
	v_mfma_f32_32x32x16_bf16 v[82:97], v[162:165], v[106:109], v[82:97]
	ds_read_b128 v[162:165], v210 offset:8704
	s_waitcnt lgkmcnt(5)
	v_mfma_f32_32x32x16_bf16 v[82:97], v[166:169], v[110:113], v[82:97]
	ds_read_b128 v[166:169], v210 offset:8736
	s_waitcnt lgkmcnt(5)
	v_mfma_f32_32x32x16_bf16 v[82:97], v[170:173], v[114:117], v[82:97]
	ds_read_b128 v[170:173], v210 offset:8768
	s_waitcnt lgkmcnt(5)
	v_mfma_f32_32x32x16_bf16 v[82:97], v[174:177], v[118:121], v[82:97]
	ds_read_b128 v[174:177], v210 offset:8800
	s_waitcnt lgkmcnt(5)
	v_mfma_f32_32x32x16_bf16 v[82:97], v[150:153], v[122:125], v[82:97]
	ds_read_b128 v[150:153], v210 offset:8832
	s_waitcnt lgkmcnt(5)
	v_mfma_f32_32x32x16_bf16 v[82:97], v[156:159], v[126:129], v[82:97]
	ds_read_b128 v[156:159], v210 offset:8864
	s_waitcnt lgkmcnt(5)
	v_mfma_f32_32x32x16_bf16 v[66:81], v[162:165], v[98:101], 0
	ds_read_b128 v[162:165], v210 offset:8896
	s_nop 8
	v_mul_f32_e32 v214, 0x3db504f3, v83
	v_mul_f32_e64 v83, |v214|, s18
	v_exp_f32_e32 v83, v83
	v_mul_f32_e32 v215, 0x3db504f3, v84
	v_mul_f32_e32 v216, 0x3db504f3, v85
	v_mul_f32_e32 v217, 0x3db504f3, v86
	v_add_f32_e32 v83, 1.0, v83
	s_waitcnt lgkmcnt(5)
	v_mfma_f32_32x32x16_bf16 v[66:81], v[166:169], v[102:105], v[66:81]
	ds_read_b128 v[166:169], v210 offset:8928
	v_mul_f32_e32 v218, 0x3db504f3, v87
	v_mul_f32_e32 v228, 0x3db504f3, v90
	v_mul_f32_e64 v85, |v228|, s18
	v_exp_f32_e32 v85, v85
	v_mul_f32_e32 v220, 0x3db504f3, v88
	v_mul_f32_e32 v221, 0x3db504f3, v89
	s_waitcnt lgkmcnt(5)
	v_mfma_f32_32x32x16_bf16 v[66:81], v[170:173], v[106:109], v[66:81]
	v_add_f32_e32 v85, 1.0, v85
	v_log_f32_e32 v85, v85
	v_max_f32_e32 v230, 0, v228
	v_mul_f32_e32 v231, 0x3db504f3, v91
	v_max_f32_e32 v226, 0, v221
	v_fmac_f32_e32 v230, 0x3f317218, v85
	s_waitcnt lgkmcnt(4)
	v_mfma_f32_32x32x16_bf16 v[66:81], v[174:177], v[110:113], v[66:81]
	v_mul_f32_e64 v85, |v231|, s18
	v_exp_f32_e32 v85, v85
	v_max_f32_e32 v232, 0, v231
	v_mul_f32_e32 v227, 0x3db504f3, v92
	v_mul_f32_e32 v229, 0x3db504f3, v93
	v_add_f32_e32 v85, 1.0, v85
	s_waitcnt lgkmcnt(3)
	v_mfma_f32_32x32x16_bf16 v[66:81], v[150:153], v[114:117], v[66:81]
	v_log_f32_e32 v85, v85
	v_mul_f32_e32 v235, 0x3db504f3, v94
	v_mul_f32_e32 v237, 0x3db504f3, v95
	v_mul_f32_e32 v238, 0x3db504f3, v96
	v_fmac_f32_e32 v232, 0x3f317218, v85
	v_add_u32_e32 v85, 0x3bd1, v140
	s_waitcnt lgkmcnt(2)
	v_mfma_f32_32x32x16_bf16 v[66:81], v[156:159], v[118:121], v[66:81]
	v_cmp_lt_i32_e64 s[10:11], v85, v130
	s_or_b64 s[10:11], s[4:5], s[10:11]
	v_mul_f32_e32 v239, 0x3db504f3, v97
	v_cndmask_b32_e64 v85, 0, -v232, s[10:11]
	v_or_b32_e32 v91, 54, v161
	v_max_f32_e32 v84, 0, v215
	s_waitcnt lgkmcnt(1)
	v_mfma_f32_32x32x16_bf16 v[66:81], v[162:165], v[122:125], v[66:81]
	v_max_f32_e32 v148, 0, v216
	v_max_f32_e32 v149, 0, v235
	v_max_f32_e32 v86, 0, v217
	v_max_f32_e32 v154, 0, v218
	v_max_f32_e32 v155, 0, v238
	v_max_f32_e32 v88, 0, v220
	s_waitcnt lgkmcnt(0)
; #define MFMA32(a, b, c) __builtin_amdgcn_mfma_f32_32x32x16_bf16((a), (b), (c), 0, 0, 0)
; template <int DQK, int MODE>
; DI void attn_core(const u16* __restrict__ Qg, int ldq, const u16* __restrict__ Kg, int ldk, const u16* __restrict__ Vtg,
;                   const u64* __restrict__ maskg, int q0, float scale, char* smem, int* sflags, f32x16 (&o)[4], float& l_run) {
;     ...
;     for (int kt = 0; kt < 2; ++kt)
; #pragma unroll
;       for (int ks = 0; ks < NKS; ++ks) {
;         const bf16x8 kf = *(const bf16x8*)(Ks + (32 * kt + krow) * KSTR + ks * 16 + hh * 8);
;         s[kt] = MFMA32(kf, qf[ks], s[kt]);
;     ...
;       const bool need_mask = (tau * 64 + 63 >= q0 + 32 * wid);
;       float tot[4], otot[4];
; #pragma unroll
;       for (int c = 0; c < 4; ++c) {
;         const int kt = c >> 1, sb = (c & 1) * 8;
;         float run = 0.f;
; #pragma unroll
;         for (int j = 0; j < 8; ++j) {
;           const int i = sb + j;
;           const float z = s[kt][i] * scale;
;           s[kt][i] = z;
;           const float e = __builtin_amdgcn_exp2f(-fabsf(z) * LOG2E);
;           const float sp = fmaxf(z, 0.f) + LN2 * __builtin_amdgcn_logf(1.f + e);
;           bool valid = true;
;           if (need_mask) valid = (kbase + 32 * kt + 16 * (i >> 3) + (i & 7)) < qrow;
;           run += valid ? -sp : 0.f;
;         }
;         tot[c] = run;
;         otot[c] = __shfl_xor(run, 32);
	v_mfma_f32_32x32x16_bf16 v[66:81], v[166:169], v[126:129], v[66:81]
	v_log_f32_e32 v144, v83
	v_mul_f32_e64 v83, |v215|, s18
	v_exp_f32_e32 v83, v83
	v_and_b32_e32 v143, 64, v0
	v_xor_b32_e32 v142, 32, v0
	v_add_u32_e32 v143, 64, v143
	v_add_f32_e32 v83, 1.0, v83
	v_log_f32_e32 v146, v83
	v_mul_f32_e64 v83, |v216|, s18
	v_exp_f32_e32 v83, v83
	s_nop 1
	v_mul_f32_e32 v242, 0x3db504f3, v66
	v_mul_f32_e64 v66, |v242|, s18
	v_exp_f32_e32 v66, v66
	v_add_f32_e32 v83, 1.0, v83
	v_log_f32_e32 v150, v83
	v_mul_f32_e64 v83, |v217|, s18
	v_exp_f32_e32 v83, v83
	v_add_f32_e32 v66, 1.0, v66
	v_log_f32_e32 v66, v66
	v_max_f32_e32 v243, 0, v242
	v_add_f32_e32 v83, 1.0, v83
	v_log_f32_e32 v152, v83
	v_mul_f32_e64 v83, |v218|, s18
	v_exp_f32_e32 v83, v83
	v_fmac_f32_e32 v243, 0x3f317218, v66
	v_sub_f32_e32 v66, 0, v243
	v_mul_f32_e32 v233, 0x3db504f3, v67
	v_add_f32_e32 v83, 1.0, v83
	v_log_f32_e32 v156, v83
	v_mul_f32_e64 v83, |v220|, s18
	v_exp_f32_e32 v83, v83
	v_mul_f32_e32 v234, 0x3db504f3, v68
	v_mul_f32_e32 v236, 0x3db504f3, v69
	v_mul_f32_e32 v244, 0x3db504f3, v70
	v_add_f32_e32 v83, 1.0, v83
	v_log_f32_e32 v158, v83
	v_mul_f32_e64 v83, |v221|, s18
	v_exp_f32_e32 v83, v83
	v_mul_f32_e32 v245, 0x3db504f3, v71
	v_mul_f32_e32 v205, 0x3db504f3, v74
	v_mul_f32_e64 v68, |v205|, s18
	v_add_f32_e32 v83, 1.0, v83
	v_log_f32_e32 v83, v83
	v_exp_f32_e32 v68, v68
	v_mul_f32_e32 v246, 0x3db504f3, v72
	v_mul_f32_e32 v247, 0x3db504f3, v73
	v_fmac_f32_e32 v226, 0x3f317218, v83
	v_add_u32_e32 v83, 0x3bc7, v140
	v_cmp_lt_i32_e64 s[6:7], v83, v130
	v_add_u32_e32 v83, 0x3bd0, v140
	s_or_b64 s[8:9], s[4:5], s[6:7]
	v_cmp_lt_i32_e64 s[6:7], v83, v130
	s_or_b64 s[6:7], s[4:5], s[6:7]
	v_sub_f32_e32 v83, 0, v230
	v_cndmask_b32_e64 v83, 0, v83, s[6:7]
	v_add_f32_e32 v83, v85, v83
	v_mul_f32_e64 v85, |v227|, s18
	v_exp_f32_e32 v85, v85
	v_add_f32_e32 v68, 1.0, v68
	v_log_f32_e32 v68, v68
	v_max_f32_e32 v222, 0, v205
	v_add_f32_e32 v85, 1.0, v85
	v_log_f32_e32 v145, v85
	v_mul_f32_e64 v85, |v229|, s18
	v_exp_f32_e32 v87, v85
	v_mul_f32_e32 v202, 0x3db504f3, v75
	v_fmac_f32_e32 v222, 0x3f317218, v68
	v_mul_f32_e64 v68, |v202|, s18
	v_add_f32_e32 v87, 1.0, v87
	v_log_f32_e32 v147, v87
	v_mul_f32_e64 v87, |v235|, s18
	v_exp_f32_e32 v87, v87
	v_exp_f32_e32 v68, v68
	v_max_f32_e32 v204, 0, v247
	v_max_f32_e32 v203, 0, v202
	v_add_f32_e32 v87, 1.0, v87
	v_log_f32_e32 v151, v87
	v_mul_f32_e64 v87, |v237|, s18
	v_exp_f32_e32 v89, v87
	v_add_f32_e32 v68, 1.0, v68
	v_log_f32_e32 v68, v68
	v_mul_f32_e32 v240, 0x3db504f3, v76
	v_add_f32_e32 v89, 1.0, v89
	v_log_f32_e32 v153, v89
	v_mul_f32_e64 v89, |v238|, s18
	v_exp_f32_e32 v89, v89
	v_fmac_f32_e32 v203, 0x3f317218, v68
	v_add_u32_e32 v68, 0x3bf1, v140
	v_cmp_lt_i32_e64 s[16:17], v68, v130
	v_add_f32_e32 v89, 1.0, v89
	v_log_f32_e32 v157, v89
	v_mul_f32_e64 v89, |v239|, s18
	v_exp_f32_e32 v90, v89
	s_or_b64 s[16:17], s[4:5], s[16:17]
	v_cndmask_b32_e64 v68, 0, -v203, s[16:17]
	v_mul_f32_e32 v241, 0x3db504f3, v77
	v_add_f32_e32 v90, 1.0, v90
	v_log_f32_e32 v159, v90
	v_add_u32_e32 v90, 0x3be0, v140
	v_cmp_lt_i32_e64 s[12:13], v90, v130
	s_or_b64 s[12:13], s[4:5], s[12:13]
	v_mul_f32_e32 v200, 0x3db504f3, v78
	v_cndmask_b32_e64 v96, 0, v66, s[12:13]
	v_mul_f32_e64 v66, |v233|, s18
	v_exp_f32_e32 v67, v66
	v_mul_f32_e32 v201, 0x3db504f3, v79
	v_mul_f32_e32 v198, 0x3db504f3, v80
	v_mul_f32_e32 v199, 0x3db504f3, v81
	v_add_f32_e32 v67, 1.0, v67
	v_log_f32_e32 v178, v67
	v_mul_f32_e64 v67, |v234|, s18
	v_exp_f32_e32 v67, v67
	v_cmp_lt_i32_e32 vcc, v142, v143
	v_or_b32_e32 v69, 33, v161
	v_max_f32_e32 v66, 0, v233
	v_add_f32_e32 v67, 1.0, v67
	v_log_f32_e32 v176, v67
	v_mul_f32_e64 v67, |v236|, s18
	v_exp_f32_e32 v67, v67
	v_cndmask_b32_e32 v0, v0, v142, vcc
	v_lshlrev_b32_e32 v219, 2, v0
	v_mul_f32_e32 v0, 0x3db504f3, v82
	v_add_f32_e32 v67, 1.0, v67
	v_log_f32_e32 v174, v67
	v_mul_f32_e64 v67, |v244|, s18
	v_exp_f32_e32 v67, v67
	v_mul_f32_e64 v82, |v0|, s18
	v_cmp_lt_i32_e64 s[20:21], v69, v130
	v_or_b32_e32 v72, 51, v161
	v_add_f32_e32 v67, 1.0, v67
	v_log_f32_e32 v168, v67
	v_mul_f32_e64 v67, |v245|, s18
	v_exp_f32_e32 v67, v67
	v_or_b32_e32 v73, 34, v161
	v_max_f32_e32 v172, 0, v234
	v_max_f32_e32 v173, 0, v241
	v_add_f32_e32 v67, 1.0, v67
	v_log_f32_e32 v166, v67
	v_mul_f32_e64 v67, |v246|, s18
	v_exp_f32_e32 v67, v67
	s_or_b64 s[22:23], s[4:5], s[20:21]
	v_cmp_lt_i32_e64 s[20:21], v72, v131
	v_cmp_lt_i32_e64 s[24:25], v73, v130
	v_add_f32_e32 v67, 1.0, v67
	v_log_f32_e32 v94, v67
	v_mul_f32_e64 v67, |v247|, s18
	v_exp_f32_e32 v67, v67
	s_or_b64 s[24:25], s[4:5], s[24:25]
	s_or_b64 s[20:21], s[4:5], s[20:21]
	v_max_f32_e32 v170, 0, v236
	v_add_f32_e32 v67, 1.0, v67
	v_log_f32_e32 v67, v67
	v_max_f32_e32 v171, 0, v200
	v_max_f32_e32 v164, 0, v244
	v_max_f32_e32 v92, 0, v246
	v_fmac_f32_e32 v204, 0x3f317218, v67
	v_add_u32_e32 v67, 0x3be7, v140
	v_cmp_lt_i32_e64 s[14:15], v67, v130
	v_add_u32_e32 v67, 0x3bf0, v140
	s_or_b64 s[26:27], s[4:5], s[14:15]
	v_cmp_lt_i32_e64 s[14:15], v67, v130
	s_or_b64 s[14:15], s[4:5], s[14:15]
	v_sub_f32_e32 v67, 0, v222
	v_cndmask_b32_e64 v67, 0, v67, s[14:15]
	v_add_f32_e32 v97, v68, v67
	v_mul_f32_e64 v67, |v240|, s18
	v_exp_f32_e32 v68, v67
	v_max_f32_e32 v67, 0, v240
	v_max_f32_e32 v165, 0, v201
	v_max_f32_e32 v93, 0, v199
	v_add_f32_e32 v68, 1.0, v68
	v_log_f32_e32 v179, v68
	v_mul_f32_e64 v68, |v241|, s18
	v_exp_f32_e32 v68, v68
	v_or_b32_e32 v140, 37, v161
	v_pk_fma_f32 v[66:67], v[178:179], s[68:69], v[66:67] op_sel_hi:[1,0,1]
	v_max_f32_e32 v162, 0, v245
	v_add_f32_e32 v68, 1.0, v68
	v_log_f32_e32 v177, v68
	v_mul_f32_e64 v68, |v200|, s18
	v_exp_f32_e32 v68, v68
	v_max_f32_e32 v163, 0, v198
; template <int DQK, int MODE>
; DI void attn_core(const u16* __restrict__ Qg, int ldq, const u16* __restrict__ Kg, int ldk, const u16* __restrict__ Vtg,
;                   const u64* __restrict__ maskg, int q0, float scale, char* smem, int* sflags, f32x16 (&o)[4], float& l_run) {
;     ...
;       for (int c = 0; c < 4; ++c) {
;         const int kt = c >> 1, sb = (c & 1) * 8;
;         float run = 0.f;
; #pragma unroll
;         for (int j = 0; j < 8; ++j) {
;           const int i = sb + j;
;           const float z = s[kt][i] * scale;
;           s[kt][i] = z;
;           const float e = __builtin_amdgcn_exp2f(-fabsf(z) * LOG2E);
;           const float sp = fmaxf(z, 0.f) + LN2 * __builtin_amdgcn_logf(1.f + e);
;           bool valid = true;
;           if (need_mask) valid = (kbase + 32 * kt + 16 * (i >> 3) + (i & 7)) < qrow;
;           run += valid ? -sp : 0.f;
;         }
;         tot[c] = run;
;         otot[c] = __shfl_xor(run, 32);
;       }
;       float rs = r_run;
; #pragma unroll
;       for (int c = 3; c >= 0; --c) {
;         const int kt = c >> 1, sb = (c & 1) * 8;
;         float run = rs + (hh == 0 ? otot[c] : 0.f);
	v_pk_fma_f32 v[70:71], v[176:177], s[68:69], v[172:173] op_sel_hi:[1,0,1]
	v_cmp_lt_i32_e64 s[38:39], v140, v130
	v_add_f32_e32 v68, 1.0, v68
	v_log_f32_e32 v175, v68
	v_mul_f32_e64 v68, |v201|, s18
	v_exp_f32_e32 v68, v68
	v_cndmask_b32_e64 v73, 0, -v71, s[20:21]
	v_cndmask_b32_e64 v72, 0, -v70, s[24:25]
	v_pk_fma_f32 v[76:77], v[174:175], s[68:69], v[170:171] op_sel_hi:[1,0,1]
	v_add_f32_e32 v68, 1.0, v68
	v_log_f32_e32 v169, v68
	v_mul_f32_e64 v68, |v198|, s18
	v_exp_f32_e32 v68, v68
	s_or_b64 s[52:53], s[4:5], s[38:39]
	v_exp_f32_e32 v82, v82
	v_cndmask_b32_e64 v90, 0, -v204, s[26:27]
	v_add_f32_e32 v68, 1.0, v68
	v_log_f32_e32 v167, v68
	v_mul_f32_e64 v68, |v199|, s18
	v_exp_f32_e32 v68, v68
	v_add_f32_e32 v82, 1.0, v82
	v_pk_fma_f32 v[162:163], v[166:167], s[68:69], v[162:163] op_sel_hi:[1,0,1]
	v_log_f32_e32 v82, v82
	v_add_f32_e32 v68, 1.0, v68
	v_log_f32_e32 v95, v68
	v_or_b32_e32 v68, 50, v161
	v_cmp_lt_i32_e64 s[18:19], v68, v131
	s_or_b64 s[18:19], s[4:5], s[18:19]
	v_cndmask_b32_e64 v68, 0, -v66, s[22:23]
	v_cndmask_b32_e64 v69, 0, -v67, s[18:19]
	v_pk_add_f32 v[74:75], v[68:69], v[96:97]
	v_pk_fma_f32 v[96:97], v[168:169], s[68:69], v[164:165] op_sel_hi:[1,0,1]
	v_pk_add_f32 v[78:79], v[72:73], v[74:75]
	v_or_b32_e32 v74, 52, v161
	v_or_b32_e32 v75, 35, v161
	v_cmp_lt_i32_e64 s[28:29], v74, v131
	v_cmp_lt_i32_e64 s[30:31], v75, v130
	s_or_b64 s[30:31], s[4:5], s[30:31]
	s_or_b64 s[28:29], s[4:5], s[28:29]
	v_cndmask_b32_e64 v75, 0, -v77, s[28:29]
	v_cndmask_b32_e64 v74, 0, -v76, s[30:31]
	v_pk_add_f32 v[80:81], v[74:75], v[78:79]
	v_or_b32_e32 v78, 53, v161
	v_or_b32_e32 v79, 36, v161
	v_cmp_lt_i32_e64 s[34:35], v78, v131
	v_cmp_lt_i32_e64 s[36:37], v79, v130
	s_or_b64 s[46:47], s[4:5], s[36:37]
	s_or_b64 s[34:35], s[4:5], s[34:35]
	v_cmp_lt_i32_e64 s[36:37], v91, v131
	v_pk_fma_f32 v[168:169], v[94:95], s[68:69], v[92:93] op_sel_hi:[1,0,1]
	v_or_b32_e32 v91, 55, v161
	v_or_b32_e32 v92, 38, v161
	v_cndmask_b32_e64 v79, 0, -v97, s[34:35]
	v_cndmask_b32_e64 v78, 0, -v96, s[46:47]
	s_or_b64 s[36:37], s[4:5], s[36:37]
	v_cmp_lt_i32_e64 s[38:39], v91, v131
	v_cmp_lt_i32_e64 s[40:41], v92, v130
	v_pk_add_f32 v[80:81], v[78:79], v[80:81]
	v_cndmask_b32_e64 v167, 0, -v163, s[36:37]
	v_cndmask_b32_e64 v166, 0, -v162, s[52:53]
	s_or_b64 s[56:57], s[4:5], s[40:41]
	s_or_b64 s[64:65], s[4:5], s[38:39]
	v_pk_add_f32 v[80:81], v[166:167], v[80:81]
	v_cndmask_b32_e64 v171, 0, -v169, s[64:65]
	v_cndmask_b32_e64 v170, 0, -v168, s[56:57]
	v_pk_add_f32 v[80:81], v[170:171], v[80:81]
	ds_bpermute_b32 v91, v219, v81
	v_max_f32_e32 v213, 0, v0
	v_or_b32_e32 v92, 1, v161
	v_fmac_f32_e32 v213, 0x3f317218, v82
	v_cmp_lt_i32_e32 vcc, v161, v130
	s_waitcnt lgkmcnt(0)
	v_pk_add_f32 v[80:81], v[90:91], v[80:81]
	ds_bpermute_b32 v140, v219, v80
	v_or_b32_e32 v90, 18, v161
	v_max_f32_e32 v142, 0, v214
	v_max_f32_e32 v143, 0, v227
	v_cmp_lt_i32_e64 s[38:39], v90, v131
	v_cmp_lt_i32_e64 s[40:41], v92, v130
	s_or_b64 vcc, s[4:5], vcc
	v_sub_f32_e32 v82, 0, v213
	s_waitcnt lgkmcnt(0)
	v_pk_add_f32 v[172:173], v[80:81], v[140:141]
	v_pk_fma_f32 v[80:81], v[144:145], s[68:69], v[142:143] op_sel_hi:[1,0,1]
	s_or_b64 s[42:43], s[4:5], s[40:41]
	s_or_b64 s[38:39], s[4:5], s[38:39]
	v_cndmask_b32_e32 v82, 0, v82, vcc
	v_max_f32_e32 v85, 0, v229
	v_cndmask_b32_e64 v93, 0, -v81, s[38:39]
	v_cndmask_b32_e64 v92, 0, -v80, s[42:43]
	v_pk_add_f32 v[94:95], v[92:93], v[82:83]
	v_pk_fma_f32 v[82:83], v[146:147], s[68:69], v[84:85] op_sel_hi:[1,0,1]
	v_or_b32_e32 v84, 19, v161
	v_or_b32_e32 v85, 2, v161
	v_cmp_lt_i32_e64 s[40:41], v84, v131
	v_cmp_lt_i32_e64 s[44:45], v85, v130
	s_or_b64 s[44:45], s[4:5], s[44:45]
	s_or_b64 s[40:41], s[4:5], s[40:41]
	v_cndmask_b32_e64 v85, 0, -v83, s[40:41]
	v_cndmask_b32_e64 v84, 0, -v82, s[44:45]
	v_pk_add_f32 v[144:145], v[84:85], v[94:95]
	v_or_b32_e32 v90, 20, v161
	v_or_b32_e32 v94, 3, v161
	v_cmp_lt_i32_e64 s[48:49], v90, v131
	v_cmp_lt_i32_e64 s[50:51], v94, v130
	v_pk_fma_f32 v[142:143], v[150:151], s[68:69], v[148:149] op_sel_hi:[1,0,1]
	s_or_b64 s[50:51], s[4:5], s[50:51]
	s_or_b64 s[48:49], s[4:5], s[48:49]
	v_cndmask_b32_e64 v95, 0, -v143, s[48:49]
	v_cndmask_b32_e64 v94, 0, -v142, s[50:51]
	v_pk_add_f32 v[146:147], v[94:95], v[144:145]
	v_or_b32_e32 v90, 21, v161
	v_or_b32_e32 v144, 4, v161
	v_max_f32_e32 v87, 0, v237
	v_cmp_lt_i32_e64 s[54:55], v90, v131
	v_cmp_lt_i32_e64 s[58:59], v144, v130
	v_pk_fma_f32 v[86:87], v[152:153], s[68:69], v[86:87] op_sel_hi:[1,0,1]
	s_or_b64 s[58:59], s[4:5], s[58:59]
	s_or_b64 s[54:55], s[4:5], s[54:55]
	v_or_b32_e32 v90, 22, v161
	v_or_b32_e32 v148, 5, v161
	v_cndmask_b32_e64 v145, 0, -v87, s[54:55]
	v_cndmask_b32_e64 v144, 0, -v86, s[58:59]
	v_cmp_lt_i32_e64 s[62:63], v90, v131
	v_cmp_lt_i32_e64 s[60:61], v148, v130
	v_pk_add_f32 v[150:151], v[144:145], v[146:147]
	v_pk_fma_f32 v[146:147], v[156:157], s[68:69], v[154:155] op_sel_hi:[1,0,1]
	s_or_b64 s[60:61], s[4:5], s[60:61]
	s_or_b64 s[66:67], s[4:5], s[62:63]
	v_cndmask_b32_e64 v149, 0, -v147, s[66:67]
	v_cndmask_b32_e64 v148, 0, -v146, s[60:61]
	v_max_f32_e32 v89, 0, v239
	v_pk_add_f32 v[152:153], v[148:149], v[150:151]
	v_or_b32_e32 v90, 23, v161
	v_or_b32_e32 v150, 6, v161
	v_pk_fma_f32 v[88:89], v[158:159], s[68:69], v[88:89] op_sel_hi:[1,0,1]
	v_cmp_lt_i32_e64 s[68:69], v90, v131
	v_cmp_lt_i32_e64 s[62:63], v150, v130
	s_or_b64 s[62:63], s[4:5], s[62:63]
	s_or_b64 s[4:5], s[4:5], s[68:69]
	v_cndmask_b32_e64 v151, 0, -v89, s[4:5]
	v_cndmask_b32_e64 v150, 0, -v88, s[62:63]
	v_pk_add_f32 v[152:153], v[150:151], v[152:153]
	ds_bpermute_b32 v161, v219, v153
	v_cndmask_b32_e64 v160, 0, -v226, s[8:9]
	v_pk_add_f32 v[164:165], v[172:173], v[172:173] op_sel:[0,1] op_sel_hi:[1,0]
	s_waitcnt lgkmcnt(0)
; template <int DQK, int MODE>
; DI void attn_core(const u16* __restrict__ Qg, int ldq, const u16* __restrict__ Kg, int ldk, const u16* __restrict__ Vtg,
;                   const u64* __restrict__ maskg, int q0, float scale, char* smem, int* sflags, f32x16 (&o)[4], float& l_run) {
;     ...
;       float rs = r_run;
; #pragma unroll
;       for (int c = 3; c >= 0; --c) {
;         const int kt = c >> 1, sb = (c & 1) * 8;
;         float run = rs + (hh == 0 ? otot[c] : 0.f);
; #pragma unroll
;         for (int j = 7; j >= 0; --j) {
;           const int i = sb + j;
;           const float z = s[kt][i];
;           const float e = __builtin_amdgcn_exp2f(-fabsf(z) * LOG2E);
;           const float sp = fmaxf(z, 0.f) + LN2 * __builtin_amdgcn_logf(1.f + e);
;           bool valid = true;
;           if (need_mask) valid = (kbase + 32 * kt + 16 * (i >> 3) + (i & 7)) < qrow;
;           const float av = __builtin_amdgcn_exp2f((z - sp + run) * LOG2E);
;           s[kt][i] = valid ? av : 0.f;
;           run += valid ? -sp : 0.f;
;         }
;         rs += tot[c] + otot[c];
;       }
;       r_run = rs;
;       const int anyv = __any(r_run >= -104.0f);
;       if (lane == 0) sflags[wid] = anyv;
;     }
; #pragma unroll
;     for (int kt = 0; kt < 2; ++kt)
; #pragma unroll
;       for (int sb = 0; sb < 2; ++sb) {
;         const bf16x8 pf = pack8(s[kt][8 * sb + 0], s[kt][8 * sb + 1], s[kt][8 * sb + 2], s[kt][8 * sb + 3],
;                                 s[kt][8 * sb + 4], s[kt][8 * sb + 5], s[kt][8 * sb + 6], s[kt][8 * sb + 7]);
	v_pk_add_f32 v[154:155], v[160:161], v[152:153]
	ds_bpermute_b32 v152, v219, v154
	v_mov_b32_e32 v153, v164
	s_waitcnt lgkmcnt(0)
	v_pk_add_f32 v[154:155], v[154:155], v[152:153]
	s_nop 0
	v_add_f32_e32 v90, v154, v155
	v_cmp_le_f32_e64 s[68:69], s33, v90
	s_and_saveexec_b64 s[78:79], s[2:3]
	s_cmp_lg_u64 s[68:69], 0
	s_cselect_b64 s[68:69], -1, 0
	v_cndmask_b32_e64 v153, 0, 1, s[68:69]
	ds_write_b32 v183, v153
	s_or_b64 exec, exec, s[78:79]
	v_cndmask_b32_e64 v91, 0, v91, s[0:1]
	v_add_f32_e32 v91, v141, v91
	v_sub_f32_e32 v141, v199, v169
	v_add_f32_e32 v141, v91, v141
	v_mul_f32_e32 v141, 0x3fb8aa3b, v141
	v_exp_f32_e32 v141, v141
	v_add_f32_e32 v91, v91, v171
	v_sub_f32_e32 v97, v201, v97
	v_sub_f32_e32 v77, v200, v77
	v_cndmask_b32_e64 v169, 0, v141, s[64:65]
	v_sub_f32_e32 v141, v198, v163
	v_add_f32_e32 v141, v141, v91
	v_add_f32_e32 v91, v167, v91
	v_add_f32_e32 v97, v97, v91
	v_add_f32_e32 v91, v79, v91
	v_add_f32_e32 v77, v77, v91
	v_mul_f32_e32 v77, 0x3fb8aa3b, v77
	v_xor_b32_e32 v156, 0x80000000, v204
	v_exp_f32_e32 v171, v77
	v_cndmask_b32_e64 v77, 0, v140, s[0:1]
	v_sub_f32_e32 v160, v247, v204
	v_cndmask_b32_e64 v156, 0, v156, s[26:27]
	v_mul_f32_e32 v97, 0x3fb8aa3b, v97
	v_add_f32_e32 v77, v77, v173
	v_exp_f32_e32 v167, v97
	v_add_f32_e32 v79, v160, v77
	v_add_f32_e32 v77, v156, v77
	v_sub_f32_e32 v97, v246, v168
	v_add_f32_e32 v97, v97, v77
	v_mul_f32_e32 v97, 0x3fb8aa3b, v97
	v_exp_f32_e32 v97, v97
	v_add_f32_e32 v77, v170, v77
	v_sub_f32_e32 v140, v245, v162
	v_sub_f32_e32 v89, v239, v89
	v_cndmask_b32_e64 v160, 0, v97, s[56:57]
	v_cndmask_b32_e64 v97, 0, v161, s[0:1]
	v_add_f32_e32 v97, v97, v164
	v_add_f32_e32 v140, v140, v77
	v_add_f32_e32 v89, v89, v97
	v_mul_f32_e32 v140, 0x3fb8aa3b, v140
	v_mul_f32_e32 v89, 0x3fb8aa3b, v89
	v_exp_f32_e32 v140, v140
	v_exp_f32_e32 v89, v89
	v_add_f32_e32 v97, v151, v97
	v_add_f32_e32 v77, v166, v77
	v_sub_f32_e32 v96, v244, v96
	v_cndmask_b32_e64 v162, 0, v140, s[52:53]
	v_sub_f32_e32 v140, v238, v147
	v_cndmask_b32_e64 v147, 0, v89, s[4:5]
	v_add_f32_e32 v89, v149, v97
	v_sub_f32_e32 v87, v237, v87
	v_add_f32_e32 v96, v96, v77
	v_add_f32_e32 v87, v87, v89
	v_mul_f32_e32 v96, 0x3fb8aa3b, v96
	v_mul_f32_e32 v87, 0x3fb8aa3b, v87
	v_exp_f32_e32 v96, v96
	v_add_f32_e32 v140, v140, v97
	v_exp_f32_e32 v97, v87
	v_add_f32_e32 v145, v145, v89
	v_sub_f32_e32 v87, v235, v143
	v_add_f32_e32 v87, v87, v145
	v_mul_f32_e32 v87, 0x3fb8aa3b, v87
	v_xor_b32_e32 v153, 0x80000000, v226
	v_mul_f32_e32 v141, 0x3fb8aa3b, v141
	v_exp_f32_e32 v149, v87
	v_cndmask_b32_e64 v87, 0, v152, s[0:1]
	v_exp_f32_e32 v163, v141
	v_cndmask_b32_e64 v166, 0, v96, s[46:47]
	v_sub_f32_e32 v96, v221, v226
	v_cndmask_b32_e64 v141, 0, v153, s[8:9]
	v_add_f32_e32 v87, v87, v155
	v_add_f32_e32 v89, v96, v87
	v_add_f32_e32 v87, v141, v87
	v_sub_f32_e32 v88, v220, v88
	v_add_f32_e32 v88, v88, v87
	v_add_f32_e32 v87, v150, v87
	v_sub_f32_e32 v96, v218, v146
	v_add_f32_e32 v96, v96, v87
	v_add_f32_e32 v87, v148, v87
	v_sub_f32_e32 v86, v217, v86
	v_add_f32_e32 v86, v86, v87
	v_mul_f32_e32 v86, 0x3fb8aa3b, v86
	v_exp_f32_e32 v86, v86
	v_sub_f32_e32 v82, v215, v82
	v_sub_f32_e32 v80, v214, v80
	v_sub_f32_e32 v0, v0, v213
	v_cndmask_b32_e64 v143, 0, v86, s[58:59]
	v_add_f32_e32 v86, v144, v87
	v_sub_f32_e32 v87, v216, v142
	v_add_f32_e32 v87, v87, v86
	v_add_f32_e32 v86, v94, v86
	v_add_f32_e32 v84, v84, v86
	v_add_f32_e32 v82, v82, v86
	v_add_f32_e32 v80, v80, v84
	v_add_f32_e32 v84, v92, v84
	v_mul_f32_e32 v82, 0x3fb8aa3b, v82
	v_mul_f32_e32 v80, 0x3fb8aa3b, v80
	v_add_f32_e32 v0, v0, v84
	v_mul_f32_e32 v140, 0x3fb8aa3b, v140
	v_mul_f32_e32 v89, 0x3fb8aa3b, v89
	v_mul_f32_e32 v88, 0x3fb8aa3b, v88
	v_mul_f32_e32 v96, 0x3fb8aa3b, v96
	v_mul_f32_e32 v87, 0x3fb8aa3b, v87
	v_exp_f32_e32 v82, v82
	v_exp_f32_e32 v80, v80
	v_mul_f32_e32 v0, 0x3fb8aa3b, v0
	v_exp_f32_e32 v140, v140
	v_exp_f32_e32 v89, v89
	v_exp_f32_e32 v88, v88
	v_exp_f32_e32 v96, v96
	v_exp_f32_e32 v87, v87
	v_exp_f32_e32 v0, v0
	v_cndmask_b32_e64 v82, 0, v82, s[44:45]
	v_cndmask_b32_e64 v80, 0, v80, s[42:43]
	v_cndmask_b32_e64 v151, 0, v140, s[66:67]
	v_cndmask_b32_e64 v140, 0, v89, s[8:9]
	v_cndmask_b32_e64 v141, 0, v88, s[62:63]
	v_cndmask_b32_e64 v96, 0, v96, s[60:61]
	v_cndmask_b32_e64 v84, 0, v87, s[50:51]
	v_cndmask_b32_e32 v0, 0, v0, vcc
	v_cvt_pk_bf16_f32 v86, v0, v80
	v_cvt_pk_bf16_f32 v87, v82, v84
	v_cvt_pk_bf16_f32 v88, v143, v96
	v_cvt_pk_bf16_f32 v89, v141, v140
	s_nop 1
	v_add_f32_e32 v80, v95, v145
	v_sub_f32_e32 v82, v229, v83
	v_add_f32_e32 v82, v82, v80
	v_add_f32_e32 v80, v85, v80
	v_sub_f32_e32 v81, v227, v81
	ds_read_b128 v[140:143], v211 offset:17408
	v_cndmask_b32_e64 v0, 0, v97, s[54:55]
	ds_read_b128 v[94:97], v211 offset:22016
	v_add_f32_e32 v81, v81, v80
	v_mul_f32_e32 v79, 0x3fb8aa3b, v79
	v_mul_f32_e32 v82, 0x3fb8aa3b, v82
	v_mul_f32_e32 v81, 0x3fb8aa3b, v81
	v_exp_f32_e32 v79, v79
	v_exp_f32_e32 v144, v82
	v_exp_f32_e32 v85, v81
	v_add_f32_e32 v92, v93, v80
	ds_read_b128 v[80:83], v211 offset:26624
	v_xor_b32_e32 v154, 0x80000000, v232
	v_cndmask_b32_e64 v156, 0, v79, s[26:27]
	v_sub_f32_e32 v79, v231, v232
	v_cndmask_b32_e64 v154, 0, v154, s[10:11]
	v_sub_f32_e32 v168, v228, v230
	v_add_f32_e32 v79, v79, v92
	v_add_f32_e32 v92, v154, v92
	v_add_f32_e32 v92, v168, v92
	s_waitcnt lgkmcnt(1)
; #define MFMA32(a, b, c) __builtin_amdgcn_mfma_f32_32x32x16_bf16((a), (b), (c), 0, 0, 0)
; template <int DQK, int MODE>
; DI void attn_core(const u16* __restrict__ Qg, int ldq, const u16* __restrict__ Kg, int ldk, const u16* __restrict__ Vtg,
;                   const u64* __restrict__ maskg, int q0, float scale, char* smem, int* sflags, f32x16 (&o)[4], float& l_run) {
;     ...
;         for (int j = 7; j >= 0; --j) {
;           const int i = sb + j;
;           const float z = s[kt][i];
;           const float e = __builtin_amdgcn_exp2f(-fabsf(z) * LOG2E);
;           const float sp = fmaxf(z, 0.f) + LN2 * __builtin_amdgcn_logf(1.f + e);
;           bool valid = true;
;           if (need_mask) valid = (kbase + 32 * kt + 16 * (i >> 3) + (i & 7)) < qrow;
;           const float av = __builtin_amdgcn_exp2f((z - sp + run) * LOG2E);
;           s[kt][i] = valid ? av : 0.f;
;           run += valid ? -sp : 0.f;
;         }
;         rs += tot[c] + otot[c];
;       }
;       r_run = rs;
;       const int anyv = __any(r_run >= -104.0f);
;       if (lane == 0) sflags[wid] = anyv;
;     }
; #pragma unroll
;     for (int kt = 0; kt < 2; ++kt)
; #pragma unroll
;       for (int sb = 0; sb < 2; ++sb) {
;         const bf16x8 pf = pack8(s[kt][8 * sb + 0], s[kt][8 * sb + 1], s[kt][8 * sb + 2], s[kt][8 * sb + 3],
;                                 s[kt][8 * sb + 4], s[kt][8 * sb + 5], s[kt][8 * sb + 6], s[kt][8 * sb + 7]);
; #pragma unroll
;         for (int t = 0; t < 4; ++t) {
;           const bf16x8 vf = *(const bf16x8*)(Vs + (32 * t + l31) * 72 + 32 * kt + 16 * sb + hh * 8);
;           o[t] = MFMA32(vf, pf, o[t]);
;         }
;       }
	v_mfma_f32_32x32x16_bf16 v[34:49], v[94:97], v[86:89], v[34:49]
	v_mul_f32_e32 v96, 0x3fb8aa3b, v92
	ds_read_b128 v[92:95], v211 offset:31232
	v_mul_f32_e32 v79, 0x3fb8aa3b, v79
	v_exp_f32_e32 v79, v79
	v_cndmask_b32_e64 v84, 0, v149, s[48:49]
	v_cndmask_b32_e64 v85, 0, v85, s[38:39]
	v_sub_f32_e32 v76, v236, v76
	s_waitcnt lgkmcnt(1)
	v_mfma_f32_32x32x16_bf16 v[18:33], v[80:83], v[86:89], v[18:33]
	v_exp_f32_e32 v80, v96
	v_cndmask_b32_e64 v96, 0, v144, s[40:41]
	v_cndmask_b32_e64 v79, 0, v79, s[10:11]
	v_sub_f32_e32 v70, v234, v70
	v_cndmask_b32_e64 v97, 0, v80, s[6:7]
	v_cvt_pk_bf16_f32 v80, v97, v79
	v_cvt_pk_bf16_f32 v81, v85, v96
	v_cvt_pk_bf16_f32 v82, v84, v0
	v_cvt_pk_bf16_f32 v83, v151, v147
	s_nop 1
	v_add_f32_e32 v0, v78, v77
	v_add_f32_e32 v76, v76, v0
	v_mul_f32_e32 v76, 0x3fb8aa3b, v76
	v_mfma_f32_32x32x16_bf16 v[50:65], v[140:143], v[86:89], v[50:65]
	ds_read_b128 v[140:143], v211 offset:17440
	v_add_f32_e32 v0, v74, v0
	v_add_f32_e32 v70, v70, v0
	v_add_f32_e32 v0, v72, v0
	v_sub_f32_e32 v66, v233, v66
	v_sub_f32_e32 v165, v242, v243
	v_add_f32_e32 v66, v66, v0
	s_waitcnt lgkmcnt(1)
	v_mfma_f32_32x32x16_bf16 v[2:17], v[92:95], v[86:89], v[2:17]
	v_exp_f32_e32 v88, v76
	ds_read_b128 v[76:79], v211 offset:22048
	ds_read_b128 v[84:87], v211 offset:26656
	v_add_f32_e32 v0, v68, v0
	v_mul_f32_e32 v66, 0x3fb8aa3b, v66
	v_add_f32_e32 v0, v165, v0
	v_mul_f32_e32 v70, 0x3fb8aa3b, v70
	s_waitcnt lgkmcnt(1)
	v_mfma_f32_32x32x16_bf16 v[34:49], v[76:79], v[80:83], v[34:49]
	ds_read_b128 v[76:79], v211 offset:31264
	v_exp_f32_e32 v66, v66
	v_mul_f32_e32 v0, 0x3fb8aa3b, v0
	v_exp_f32_e32 v70, v70
	v_exp_f32_e32 v0, v0
	v_cndmask_b32_e64 v66, 0, v66, s[22:23]
	v_cndmask_b32_e64 v68, 0, v88, s[30:31]
	s_waitcnt lgkmcnt(1)
	v_mfma_f32_32x32x16_bf16 v[18:33], v[84:87], v[80:83], v[18:33]
	v_cndmask_b32_e64 v70, 0, v70, s[24:25]
	v_cndmask_b32_e64 v0, 0, v0, s[12:13]
	v_cvt_pk_bf16_f32 v84, v0, v66
	v_cvt_pk_bf16_f32 v85, v70, v68
	v_cvt_pk_bf16_f32 v86, v166, v162
	v_cvt_pk_bf16_f32 v87, v160, v156
	s_nop 1
	ds_read_b128 v[92:95], v211 offset:17472
	v_add_f32_e32 v66, v75, v91
	v_sub_f32_e32 v68, v241, v71
	v_add_f32_e32 v68, v68, v66
	s_waitcnt lgkmcnt(1)
	v_mfma_f32_32x32x16_bf16 v[2:17], v[76:79], v[80:83], v[2:17]
	ds_read_b128 v[74:77], v211 offset:22080
	v_add_f32_e32 v66, v73, v66
	ds_read_b128 v[70:73], v211 offset:26688
	v_sub_f32_e32 v67, v240, v67
	v_add_f32_e32 v67, v67, v66
	v_sub_f32_e32 v158, v202, v203
	v_mul_f32_e32 v67, 0x3fb8aa3b, v67
	v_add_f32_e32 v66, v69, v66
	v_xor_b32_e32 v157, 0x80000000, v203
	v_mfma_f32_32x32x16_bf16 v[50:65], v[140:143], v[80:83], v[50:65]
	v_cndmask_b32_e64 v157, 0, v157, s[16:17]
	v_mul_f32_e32 v68, 0x3fb8aa3b, v68
	v_exp_f32_e32 v80, v68
	v_sub_f32_e32 v159, v205, v222
	v_cndmask_b32_e64 v0, 0, v163, s[36:37]
	v_cndmask_b32_e64 v78, 0, v167, s[34:35]
	v_cndmask_b32_e64 v79, 0, v171, s[28:29]
	s_waitcnt lgkmcnt(1)
	v_mfma_f32_32x32x16_bf16 v[34:49], v[74:77], v[84:87], v[34:49]
	v_exp_f32_e32 v74, v67
	v_add_f32_e32 v67, v158, v66
	v_mul_f32_e32 v67, 0x3fb8aa3b, v67
	v_exp_f32_e32 v75, v67
	v_add_f32_e32 v76, v157, v66
	ds_read_b128 v[66:69], v211 offset:31296
	s_waitcnt lgkmcnt(1)
	v_mfma_f32_32x32x16_bf16 v[18:33], v[70:73], v[84:87], v[18:33]
	v_add_f32_e32 v70, v159, v76
	v_mul_f32_e32 v70, 0x3fb8aa3b, v70
	v_exp_f32_e32 v70, v70
	v_cndmask_b32_e64 v71, 0, v80, s[20:21]
	v_cndmask_b32_e64 v72, 0, v74, s[18:19]
	v_cndmask_b32_e64 v73, 0, v75, s[16:17]
	v_cndmask_b32_e64 v70, 0, v70, s[14:15]
	v_mfma_f32_32x32x16_bf16 v[50:65], v[92:95], v[84:87], v[50:65]
	s_waitcnt lgkmcnt(0)
	v_mfma_f32_32x32x16_bf16 v[2:17], v[66:69], v[84:87], v[2:17]
	v_cvt_pk_bf16_f32 v66, v70, v73
	v_cvt_pk_bf16_f32 v67, v72, v71
	v_cvt_pk_bf16_f32 v68, v79, v78
	v_cvt_pk_bf16_f32 v69, v0, v169
	s_nop 1
	ds_read_b128 v[70:73], v211 offset:17504
	ds_read_b128 v[74:77], v211 offset:22112
	s_waitcnt lgkmcnt(1)
	v_mfma_f32_32x32x16_bf16 v[50:65], v[70:73], v[66:69], v[50:65]
	s_waitcnt lgkmcnt(0)
	v_mfma_f32_32x32x16_bf16 v[34:49], v[74:77], v[66:69], v[34:49]
	ds_read_b128 v[70:73], v211 offset:26720
	ds_read_b128 v[74:77], v211 offset:31328
	s_waitcnt lgkmcnt(1)
	v_mfma_f32_32x32x16_bf16 v[18:33], v[70:73], v[66:69], v[18:33]
	s_waitcnt lgkmcnt(0)
	v_mfma_f32_32x32x16_bf16 v[2:17], v[74:77], v[66:69], v[2:17]
